# v12 + FFN-out L0 / W_O residual epilogues: second half's residual loads issued together with the first half's (one memory round trip per tile instead of two)
# baseline (speedup 1.0000x reference)
.LBB0_717:
	s_lshl_b32 s0, s43, 8
	v_mov_b32_e32 v128, v175
	v_mov_b32_e32 v194, v174
	s_add_i32 s0, s0, s30
	v_mov_b32_e32 v131, v161
	v_add_u32_e32 v181, s0, v128
	s_lshl_b32 s0, s42, 8
	s_or_b32 s0, s0, s31
	v_lshl_add_u32 v170, v194, 3, s0
	v_ashrrev_i32_e32 v171, 31, v170
	v_lshlrev_b32_e32 v160, 11, v181
	v_lshl_add_u64 v[172:173], v[170:171], 1, s[72:73]
	v_lshl_add_u64 v[128:129], v[160:161], 1, v[172:173]
	global_load_dwordx4 v[186:189], v[128:129], off
	global_load_dwordx4 v[190:193], v[128:129], off offset:256
	v_mov_b32_e32 v129, v161
	v_add_u32_e32 v128, 0x8000, v160
	v_add_u32_e32 v130, 0x10000, v160
	v_mov_b32_e32 v133, v161
	v_add_u32_e32 v132, 0x18000, v160
	v_lshl_add_u64 v[128:129], v[128:129], 1, v[172:173]
	v_lshl_add_u64 v[130:131], v[130:131], 1, v[172:173]
	v_lshl_add_u64 v[182:183], v[132:133], 1, v[172:173]
	global_load_dwordx4 v[148:151], v[128:129], off
	global_load_dwordx4 v[144:147], v[128:129], off offset:256
	global_load_dwordx4 v[140:143], v[130:131], off
	global_load_dwordx4 v[136:139], v[130:131], off offset:256
	global_load_dwordx4 v[132:135], v[182:183], off
	s_nop 0
	global_load_dwordx4 v[128:131], v[182:183], off offset:256
	v_and_b32_e32 v182, 64, v180
	v_mov_b32_e32 v183, v161
	v_add_u32_e32 v204, 64, v182
	v_add_u32_e32 v182, v160, v170
	v_cmp_eq_u32_e32 vcc, 0, v194
	v_lshl_add_u64 v[194:195], v[182:183], 1, s[72:73]
	s_lshl_b32 s0, s42, 2
	v_xor_b32_e32 v171, 16, v180
	s_or_b32 s16, s0, s29
	v_cmp_lt_i32_e64 s[0:1], v171, v204
	v_add_u32_e32 v252, 0x40000, v160
	v_mov_b32_e32 v253, v161
	v_lshl_add_u64 v[252:253], v[252:253], 1, v[172:173]
	global_load_dwordx4 v[220:223], v[252:253], off
	global_load_dwordx4 v[224:227], v[252:253], off offset:256
	v_add_u32_e32 v252, 0x48000, v160
	v_mov_b32_e32 v253, v161
	v_lshl_add_u64 v[252:253], v[252:253], 1, v[172:173]
	global_load_dwordx4 v[228:231], v[252:253], off
	global_load_dwordx4 v[232:235], v[252:253], off offset:256
	v_add_u32_e32 v252, 0x50000, v160
	v_mov_b32_e32 v253, v161
	v_lshl_add_u64 v[252:253], v[252:253], 1, v[172:173]
	global_load_dwordx4 v[236:239], v[252:253], off
	global_load_dwordx4 v[240:243], v[252:253], off offset:256
	v_add_u32_e32 v252, 0x58000, v160
	v_mov_b32_e32 v253, v161
	v_lshl_add_u64 v[252:253], v[252:253], 1, v[172:173]
	global_load_dwordx4 v[244:247], v[252:253], off
	global_load_dwordx4 v[248:251], v[252:253], off offset:256
	s_waitcnt vmcnt(0)
	v_lshlrev_b32_e32 v196, 16, v186
	v_and_b32_e32 v197, 0xffff0000, v186
	v_lshlrev_b32_e32 v186, 16, v187
	v_and_b32_e32 v187, 0xffff0000, v187
	v_lshlrev_b32_e32 v198, 16, v188
	v_and_b32_e32 v199, 0xffff0000, v188
	v_lshlrev_b32_e32 v188, 16, v189
	v_and_b32_e32 v189, 0xffff0000, v189
	v_lshlrev_b32_e32 v200, 16, v190
	v_and_b32_e32 v201, 0xffff0000, v190
	v_lshlrev_b32_e32 v190, 16, v191
	v_and_b32_e32 v191, 0xffff0000, v191
	v_lshlrev_b32_e32 v202, 16, v192
	v_and_b32_e32 v203, 0xffff0000, v192
	v_lshlrev_b32_e32 v192, 16, v193
	v_and_b32_e32 v193, 0xffff0000, v193
	v_pk_add_f32 v[126:127], v[126:127], v[186:187]
	v_pk_add_f32 v[124:125], v[124:125], v[196:197]
	v_pk_add_f32 v[122:123], v[122:123], v[188:189]
	v_pk_add_f32 v[120:121], v[120:121], v[198:199]
	v_pk_add_f32 v[118:119], v[118:119], v[190:191]
	v_pk_add_f32 v[116:117], v[116:117], v[200:201]
	v_pk_add_f32 v[186:187], v[114:115], v[192:193]
	v_pk_add_f32 v[188:189], v[112:113], v[202:203]
	v_cvt_pk_bf16_f32 v112, v124, v125
	v_cvt_pk_bf16_f32 v113, v126, v127
	v_cvt_pk_bf16_f32 v114, v120, v121
	v_cvt_pk_bf16_f32 v115, v122, v123
	v_mul_f32_e32 v125, v125, v125
	v_mul_f32_e32 v127, v127, v127
	v_mul_f32_e32 v121, v121, v121
	v_mul_f32_e32 v123, v123, v123
	v_mul_f32_e32 v183, v117, v117
	v_mul_f32_e32 v190, v119, v119
	v_mul_f32_e32 v191, v189, v189
	v_mul_f32_e32 v192, v187, v187
	v_fmac_f32_e32 v125, v124, v124
	v_fmac_f32_e32 v127, v126, v126
	v_fmac_f32_e32 v121, v120, v120
	v_fmac_f32_e32 v123, v122, v122
	v_fmac_f32_e32 v183, v116, v116
	v_fmac_f32_e32 v190, v118, v118
	v_fmac_f32_e32 v191, v188, v188
	v_fmac_f32_e32 v192, v186, v186
	global_store_dwordx4 v[194:195], v[112:115], off
	v_cndmask_b32_e64 v171, v180, v171, s[0:1]
	v_add_u32_e32 v120, 0x80, v182
	v_add_f32_e32 v112, v125, v127
	v_add_f32_e32 v113, v121, v123
	v_add_f32_e32 v114, v183, v190
	v_add_f32_e32 v115, v191, v192
	v_add_f32_e32 v112, v112, v113
	v_add_f32_e32 v113, v114, v115
	v_add_f32_e32 v113, v112, v113
	v_lshlrev_b32_e32 v112, 2, v171
	v_mov_b32_e32 v121, v161
	v_lshl_add_u64 v[120:121], v[120:121], 1, s[72:73]
	v_cvt_pk_bf16_f32 v116, v116, v117
	v_cvt_pk_bf16_f32 v117, v118, v119
	s_waitcnt lgkmcnt(0)
	v_mov_b32_e32 v114, v113
	v_mov_b32_e32 v253, v113
	s_nop 1
	v_permlane16_swap_b32_e32 v114, v253
	v_add_f32_e32 v114, v114, v253
	v_xor_b32_e32 v113, 32, v180
	v_cmp_lt_i32_e64 s[0:1], v113, v204
	v_cvt_pk_bf16_f32 v118, v188, v189
	v_cvt_pk_bf16_f32 v119, v186, v187
	global_store_dwordx4 v[120:121], v[116:119], off
	s_nop 0
	v_cndmask_b32_e64 v113, v180, v113, s[0:1]
	v_lshlrev_b32_e32 v113, 2, v113
	v_mov_b32_e32 v115, v114
	v_mov_b32_e32 v253, v114
	s_nop 1
	v_permlane32_swap_b32_e32 v115, v253
	v_add_f32_e32 v116, v115, v253
	s_and_saveexec_b64 s[0:1], vcc
	s_cbranch_execz .LBB0_719
	s_waitcnt lgkmcnt(0)
	v_lshl_add_u32 v114, v181, 5, s16
	v_mov_b32_e32 v115, v161
	v_lshl_add_u64 v[114:115], v[114:115], 2, s[76:77]
	global_store_dword v[114:115], v116, off

.LBB0_725:
	s_or_b64 exec, exec, s[0:1]
	v_add_u32_e32 v64, 0x40000, v160
	s_waitcnt lgkmcnt(0)
	v_mov_b32_e32 v65, v161
	v_lshl_add_u64 v[64:65], v[64:65], 1, v[172:173]
	v_add_u32_e32 v64, 0x48000, v160
	v_mov_b32_e32 v65, v161
	v_add_u32_e32 v66, 0x50000, v160
	v_mov_b32_e32 v67, v161
	v_add_u32_e32 v160, 0x58000, v160
	v_lshl_add_u64 v[64:65], v[64:65], 1, v[172:173]
	v_lshl_add_u64 v[66:67], v[66:67], 1, v[172:173]
	v_lshl_add_u64 v[88:89], v[160:161], 1, v[172:173]
	s_nop 0
	v_add_u32_e32 v88, 0x80, v181
	v_lshl_add_u32 v160, v88, 11, v170
	v_lshl_add_u64 v[98:99], v[160:161], 1, s[72:73]
	v_add_u32_e32 v160, 0x80, v160
	s_waitcnt vmcnt(7)
	v_lshlrev_b32_e32 v100, 16, v220
	v_and_b32_e32 v101, 0xffff0000, v220
	v_lshlrev_b32_e32 v220, 16, v221
	v_and_b32_e32 v221, 0xffff0000, v221
	v_lshlrev_b32_e32 v102, 16, v222
	v_and_b32_e32 v103, 0xffff0000, v222
	v_lshlrev_b32_e32 v222, 16, v223
	v_and_b32_e32 v223, 0xffff0000, v223
	s_waitcnt vmcnt(6)
	v_lshlrev_b32_e32 v104, 16, v224
	v_and_b32_e32 v105, 0xffff0000, v224
	v_lshlrev_b32_e32 v224, 16, v225
	v_and_b32_e32 v225, 0xffff0000, v225
	v_lshlrev_b32_e32 v106, 16, v226
	v_and_b32_e32 v107, 0xffff0000, v226
	v_lshlrev_b32_e32 v226, 16, v227
	v_and_b32_e32 v227, 0xffff0000, v227
	v_pk_add_f32 v[62:63], v[62:63], v[220:221]
	v_pk_add_f32 v[60:61], v[60:61], v[100:101]
	v_pk_add_f32 v[58:59], v[58:59], v[222:223]
	v_pk_add_f32 v[56:57], v[56:57], v[102:103]
	v_pk_add_f32 v[54:55], v[54:55], v[224:225]
	v_pk_add_f32 v[52:53], v[52:53], v[104:105]
	v_pk_add_f32 v[220:221], v[50:51], v[226:227]
	v_pk_add_f32 v[222:223], v[48:49], v[106:107]
	v_cvt_pk_bf16_f32 v48, v60, v61
	v_cvt_pk_bf16_f32 v49, v62, v63
	v_cvt_pk_bf16_f32 v50, v56, v57
	v_cvt_pk_bf16_f32 v51, v58, v59
	v_mul_f32_e32 v61, v61, v61
	v_mul_f32_e32 v63, v63, v63
	v_mul_f32_e32 v57, v57, v57
	v_mul_f32_e32 v59, v59, v59
	v_mul_f32_e32 v89, v53, v53
	v_mul_f32_e32 v224, v55, v55
	v_mul_f32_e32 v225, v223, v223
	v_mul_f32_e32 v226, v221, v221
	v_fmac_f32_e32 v61, v60, v60
	v_fmac_f32_e32 v63, v62, v62
	v_fmac_f32_e32 v57, v56, v56
	v_fmac_f32_e32 v59, v58, v58
	v_fmac_f32_e32 v89, v52, v52
	v_fmac_f32_e32 v224, v54, v54
	v_fmac_f32_e32 v225, v222, v222
	v_fmac_f32_e32 v226, v220, v220
	v_add_f32_e32 v56, v61, v63
	v_add_f32_e32 v57, v57, v59
	v_add_f32_e32 v58, v89, v224
	v_add_f32_e32 v59, v225, v226
	v_add_f32_e32 v56, v56, v57
	v_add_f32_e32 v57, v58, v59
	v_add_f32_e32 v56, v56, v57
	global_store_dwordx4 v[98:99], v[48:51], off
	s_nop 1
	v_cvt_pk_bf16_f32 v50, v52, v53
	s_waitcnt lgkmcnt(0)
	v_mov_b32_e32 v57, v56
	v_mov_b32_e32 v253, v56
	s_nop 1
	v_permlane16_swap_b32_e32 v57, v253
	v_add_f32_e32 v48, v57, v253
	v_cvt_pk_bf16_f32 v51, v54, v55
	v_lshl_add_u64 v[54:55], v[160:161], 1, s[72:73]
	v_cvt_pk_bf16_f32 v52, v222, v223
	v_cvt_pk_bf16_f32 v53, v220, v221
	global_store_dwordx4 v[54:55], v[50:53], off
	v_mov_b32_e32 v49, v48
	v_mov_b32_e32 v253, v48
	s_nop 1
	v_permlane32_swap_b32_e32 v49, v253
	v_add_f32_e32 v50, v49, v253
	s_and_saveexec_b64 s[0:1], vcc
	s_cbranch_execz .LBB0_727
	v_lshl_add_u32 v160, v88, 5, s16
	s_waitcnt lgkmcnt(0)
	v_lshl_add_u64 v[48:49], v[160:161], 2, s[76:77]
	global_store_dword v[48:49], v50, off
.LBB0_727:
	s_or_b64 exec, exec, s[0:1]
	s_waitcnt vmcnt(7)
	v_lshlrev_b32_e32 v50, 16, v228
	v_and_b32_e32 v51, 0xffff0000, v228
	v_lshlrev_b32_e32 v52, 16, v229
	v_and_b32_e32 v53, 0xffff0000, v229
	v_lshlrev_b32_e32 v54, 16, v230
	v_and_b32_e32 v55, 0xffff0000, v230
	v_pk_add_f32 v[44:45], v[44:45], v[50:51]
	v_pk_add_f32 v[46:47], v[46:47], v[52:53]
	v_pk_add_f32 v[52:53], v[40:41], v[54:55]
	v_cvt_pk_bf16_f32 v40, v44, v45
	v_mul_f32_e32 v45, v45, v45
	v_lshlrev_b32_e32 v56, 16, v231
	v_and_b32_e32 v57, 0xffff0000, v231
	v_fmac_f32_e32 v45, v44, v44
	v_mul_f32_e32 v44, v47, v47
	v_pk_add_f32 v[50:51], v[42:43], v[56:57]
	v_fmac_f32_e32 v44, v46, v46
	v_cvt_pk_bf16_f32 v41, v46, v47
	v_add_f32_e32 v44, v45, v44
	v_mul_f32_e32 v45, v53, v53
	v_mul_f32_e32 v46, v51, v51
	v_fmac_f32_e32 v45, v52, v52
	v_fmac_f32_e32 v46, v50, v50
	v_add_f32_e32 v45, v45, v46
	s_waitcnt lgkmcnt(0)
	v_add_f32_e32 v49, v44, v45
	s_waitcnt vmcnt(6)
	v_lshlrev_b32_e32 v44, 16, v232
	v_and_b32_e32 v45, 0xffff0000, v232
	v_lshlrev_b32_e32 v46, 16, v233
	v_and_b32_e32 v47, 0xffff0000, v233
	v_cvt_pk_bf16_f32 v42, v52, v53
	v_cvt_pk_bf16_f32 v43, v50, v51
	v_lshlrev_b32_e32 v50, 16, v234
	v_and_b32_e32 v51, 0xffff0000, v234
	v_pk_add_f32 v[38:39], v[38:39], v[46:47]
	v_pk_add_f32 v[36:37], v[36:37], v[44:45]
	v_lshlrev_b32_e32 v52, 16, v235
	v_and_b32_e32 v53, 0xffff0000, v235
	v_pk_add_f32 v[46:47], v[32:33], v[50:51]
	v_mul_f32_e32 v32, v37, v37
	v_mul_f32_e32 v33, v39, v39
	v_pk_add_f32 v[44:45], v[34:35], v[52:53]
	v_fmac_f32_e32 v32, v36, v36
	v_fmac_f32_e32 v33, v38, v38
	v_add_f32_e32 v32, v32, v33
	v_mul_f32_e32 v33, v47, v47
	v_mul_f32_e32 v34, v45, v45
	v_fmac_f32_e32 v33, v46, v46
	v_fmac_f32_e32 v34, v44, v44
	v_add_f32_e32 v33, v33, v34
	v_add_f32_e32 v32, v32, v33
	v_add_f32_e32 v32, v49, v32
	v_add_u32_e32 v48, 0x90, v181
	v_lshl_add_u32 v160, v48, 11, v170
	v_lshl_add_u64 v[54:55], v[160:161], 1, s[72:73]
	v_add_u32_e32 v160, 0x80, v160
	s_waitcnt lgkmcnt(0)
	v_mov_b32_e32 v33, v32
	v_mov_b32_e32 v253, v32
	s_nop 1
	v_permlane16_swap_b32_e32 v33, v253
	v_add_f32_e32 v32, v33, v253
	global_store_dwordx4 v[54:55], v[40:43], off
	v_cvt_pk_bf16_f32 v34, v36, v37
	v_cvt_pk_bf16_f32 v35, v38, v39
	v_lshl_add_u64 v[38:39], v[160:161], 1, s[72:73]
	v_cvt_pk_bf16_f32 v36, v46, v47
	v_cvt_pk_bf16_f32 v37, v44, v45
	global_store_dwordx4 v[38:39], v[34:37], off
	v_mov_b32_e32 v33, v32
	v_mov_b32_e32 v253, v32
	s_nop 1
	v_permlane32_swap_b32_e32 v33, v253
	v_add_f32_e32 v34, v33, v253
	s_and_saveexec_b64 s[0:1], vcc
	s_cbranch_execz .LBB0_729
	v_lshl_add_u32 v160, v48, 5, s16
	s_waitcnt lgkmcnt(0)
	v_lshl_add_u64 v[32:33], v[160:161], 2, s[76:77]
	global_store_dword v[32:33], v34, off
.LBB0_729:
	s_or_b64 exec, exec, s[0:1]
	s_waitcnt vmcnt(7)
	v_lshlrev_b32_e32 v34, 16, v236
	v_and_b32_e32 v35, 0xffff0000, v236
	v_lshlrev_b32_e32 v36, 16, v237
	v_and_b32_e32 v37, 0xffff0000, v237
	v_lshlrev_b32_e32 v38, 16, v238
	v_and_b32_e32 v39, 0xffff0000, v238
	v_pk_add_f32 v[28:29], v[28:29], v[34:35]
	v_pk_add_f32 v[30:31], v[30:31], v[36:37]
	v_pk_add_f32 v[36:37], v[24:25], v[38:39]
	v_cvt_pk_bf16_f32 v24, v28, v29
	v_mul_f32_e32 v29, v29, v29
	v_lshlrev_b32_e32 v40, 16, v239
	v_and_b32_e32 v41, 0xffff0000, v239
	v_fmac_f32_e32 v29, v28, v28
	v_mul_f32_e32 v28, v31, v31
	v_pk_add_f32 v[34:35], v[26:27], v[40:41]
	v_fmac_f32_e32 v28, v30, v30
	v_cvt_pk_bf16_f32 v25, v30, v31
	v_add_f32_e32 v28, v29, v28
	v_mul_f32_e32 v29, v37, v37
	v_mul_f32_e32 v30, v35, v35
	v_fmac_f32_e32 v29, v36, v36
	v_fmac_f32_e32 v30, v34, v34
	v_add_f32_e32 v29, v29, v30
	s_waitcnt lgkmcnt(0)
	v_add_f32_e32 v33, v28, v29
	s_waitcnt vmcnt(6)
	v_lshlrev_b32_e32 v28, 16, v240
	v_and_b32_e32 v29, 0xffff0000, v240
	v_lshlrev_b32_e32 v30, 16, v241
	v_and_b32_e32 v31, 0xffff0000, v241
	v_cvt_pk_bf16_f32 v26, v36, v37
	v_cvt_pk_bf16_f32 v27, v34, v35
	v_lshlrev_b32_e32 v34, 16, v242
	v_and_b32_e32 v35, 0xffff0000, v242
	v_pk_add_f32 v[22:23], v[22:23], v[30:31]
	v_pk_add_f32 v[20:21], v[20:21], v[28:29]
	v_lshlrev_b32_e32 v36, 16, v243
	v_and_b32_e32 v37, 0xffff0000, v243
	v_pk_add_f32 v[30:31], v[16:17], v[34:35]
	v_mul_f32_e32 v16, v21, v21
	v_mul_f32_e32 v17, v23, v23
	v_pk_add_f32 v[28:29], v[18:19], v[36:37]
	v_fmac_f32_e32 v16, v20, v20
	v_fmac_f32_e32 v17, v22, v22
	v_add_f32_e32 v16, v16, v17
	v_mul_f32_e32 v17, v31, v31
	v_mul_f32_e32 v18, v29, v29
	v_fmac_f32_e32 v17, v30, v30
	v_fmac_f32_e32 v18, v28, v28
	v_add_f32_e32 v17, v17, v18
	v_add_f32_e32 v16, v16, v17
	v_add_f32_e32 v16, v33, v16
	v_add_u32_e32 v32, 0xa0, v181
	v_lshl_add_u32 v160, v32, 11, v170
	v_lshl_add_u64 v[38:39], v[160:161], 1, s[72:73]
	v_add_u32_e32 v160, 0x80, v160
	s_waitcnt lgkmcnt(0)
	v_mov_b32_e32 v17, v16
	v_mov_b32_e32 v253, v16
	s_nop 1
	v_permlane16_swap_b32_e32 v17, v253
	v_add_f32_e32 v16, v17, v253
	global_store_dwordx4 v[38:39], v[24:27], off
	v_cvt_pk_bf16_f32 v18, v20, v21
	v_cvt_pk_bf16_f32 v19, v22, v23
	v_lshl_add_u64 v[22:23], v[160:161], 1, s[72:73]
	v_cvt_pk_bf16_f32 v20, v30, v31
	v_cvt_pk_bf16_f32 v21, v28, v29
	global_store_dwordx4 v[22:23], v[18:21], off
	v_mov_b32_e32 v17, v16
	v_mov_b32_e32 v253, v16
	s_nop 1
	v_permlane32_swap_b32_e32 v17, v253
	v_add_f32_e32 v18, v17, v253
	s_and_saveexec_b64 s[0:1], vcc
	s_cbranch_execz .LBB0_731
	v_lshl_add_u32 v160, v32, 5, s16
	s_waitcnt lgkmcnt(0)
	v_lshl_add_u64 v[16:17], v[160:161], 2, s[76:77]
	global_store_dword v[16:17], v18, off
.LBB0_731:
	s_or_b64 exec, exec, s[0:1]
	s_waitcnt vmcnt(7)
	v_lshlrev_b32_e32 v18, 16, v244
	v_and_b32_e32 v19, 0xffff0000, v244
	v_lshlrev_b32_e32 v20, 16, v245
	v_and_b32_e32 v21, 0xffff0000, v245
	v_lshlrev_b32_e32 v22, 16, v246
	v_and_b32_e32 v23, 0xffff0000, v246
	v_pk_add_f32 v[12:13], v[12:13], v[18:19]
	v_pk_add_f32 v[14:15], v[14:15], v[20:21]
	v_pk_add_f32 v[20:21], v[8:9], v[22:23]
	v_cvt_pk_bf16_f32 v8, v12, v13
	v_mul_f32_e32 v13, v13, v13
	v_lshlrev_b32_e32 v24, 16, v247
	v_and_b32_e32 v25, 0xffff0000, v247
	v_fmac_f32_e32 v13, v12, v12
	v_mul_f32_e32 v12, v15, v15
	v_pk_add_f32 v[18:19], v[10:11], v[24:25]
	v_fmac_f32_e32 v12, v14, v14
	v_cvt_pk_bf16_f32 v9, v14, v15
	v_add_f32_e32 v12, v13, v12
	v_mul_f32_e32 v13, v21, v21
	v_mul_f32_e32 v14, v19, v19
	v_fmac_f32_e32 v13, v20, v20
	v_fmac_f32_e32 v14, v18, v18
	v_add_f32_e32 v13, v13, v14
	s_waitcnt lgkmcnt(0)
	v_add_f32_e32 v17, v12, v13
	s_waitcnt vmcnt(6)
	v_lshlrev_b32_e32 v12, 16, v248
	v_and_b32_e32 v13, 0xffff0000, v248
	v_lshlrev_b32_e32 v14, 16, v249
	v_and_b32_e32 v15, 0xffff0000, v249
	v_cvt_pk_bf16_f32 v10, v20, v21
	v_cvt_pk_bf16_f32 v11, v18, v19
	v_lshlrev_b32_e32 v18, 16, v250
	v_and_b32_e32 v19, 0xffff0000, v250
	v_pk_add_f32 v[6:7], v[6:7], v[14:15]
	v_pk_add_f32 v[4:5], v[4:5], v[12:13]
	v_lshlrev_b32_e32 v20, 16, v251
	v_and_b32_e32 v21, 0xffff0000, v251
	v_pk_add_f32 v[14:15], v[0:1], v[18:19]
	v_mul_f32_e32 v0, v5, v5
	v_mul_f32_e32 v1, v7, v7
	v_pk_add_f32 v[12:13], v[2:3], v[20:21]
	v_fmac_f32_e32 v0, v4, v4
	v_fmac_f32_e32 v1, v6, v6
	v_add_f32_e32 v0, v0, v1
	v_mul_f32_e32 v1, v15, v15
	v_mul_f32_e32 v2, v13, v13
	v_fmac_f32_e32 v1, v14, v14
	v_fmac_f32_e32 v2, v12, v12
	v_add_f32_e32 v1, v1, v2
	v_add_f32_e32 v0, v0, v1
	v_add_f32_e32 v0, v17, v0
	v_add_u32_e32 v16, 0xb0, v181
	v_lshl_add_u32 v160, v16, 11, v170
	v_lshl_add_u64 v[22:23], v[160:161], 1, s[72:73]
	v_add_u32_e32 v160, 0x80, v160
	s_waitcnt lgkmcnt(0)
	v_mov_b32_e32 v1, v0
	v_mov_b32_e32 v253, v0
	s_nop 1
	v_permlane16_swap_b32_e32 v1, v253
	v_add_f32_e32 v0, v1, v253
	global_store_dwordx4 v[22:23], v[8:11], off
	v_cvt_pk_bf16_f32 v2, v4, v5
	v_cvt_pk_bf16_f32 v3, v6, v7
	v_lshl_add_u64 v[6:7], v[160:161], 1, s[72:73]
	v_cvt_pk_bf16_f32 v4, v14, v15
	v_cvt_pk_bf16_f32 v5, v12, v13
	global_store_dwordx4 v[6:7], v[2:5], off
	v_mov_b32_e32 v1, v0
	v_mov_b32_e32 v253, v0
	s_nop 1
	v_permlane32_swap_b32_e32 v1, v253
	v_add_f32_e32 v2, v1, v253
	s_and_saveexec_b64 s[0:1], vcc
	s_cbranch_execz .LBB0_733
	v_lshl_add_u32 v160, v16, 5, s16
	s_waitcnt lgkmcnt(0)
	v_lshl_add_u64 v[0:1], v[160:161], 2, s[76:77]
	global_store_dword v[0:1], v2, off

.LBB0_1283:
	s_lshl_b32 s1, s20, 8
	v_mov_b32_e32 v128, v175
	v_mov_b32_e32 v194, v174
	s_add_i32 s1, s1, s35
	v_mov_b32_e32 v131, v161
	v_add_u32_e32 v181, s1, v128
	s_lshl_b32 s1, s0, 8
	s_or_b32 s1, s1, s36
	v_lshl_add_u32 v170, v194, 3, s1
	v_ashrrev_i32_e32 v171, 31, v170
	v_lshlrev_b32_e32 v160, 11, v181
	v_lshl_add_u64 v[172:173], v[170:171], 1, s[72:73]
	v_lshl_add_u64 v[128:129], v[160:161], 1, v[172:173]
	global_load_dwordx4 v[186:189], v[128:129], off
	global_load_dwordx4 v[190:193], v[128:129], off offset:256
	v_mov_b32_e32 v129, v161
	v_add_u32_e32 v128, 0x8000, v160
	v_add_u32_e32 v130, 0x10000, v160
	v_mov_b32_e32 v133, v161
	v_add_u32_e32 v132, 0x18000, v160
	v_lshl_add_u64 v[128:129], v[128:129], 1, v[172:173]
	v_lshl_add_u64 v[130:131], v[130:131], 1, v[172:173]
	v_lshl_add_u64 v[182:183], v[132:133], 1, v[172:173]
	global_load_dwordx4 v[148:151], v[128:129], off
	global_load_dwordx4 v[144:147], v[128:129], off offset:256
	global_load_dwordx4 v[140:143], v[130:131], off
	global_load_dwordx4 v[136:139], v[130:131], off offset:256
	global_load_dwordx4 v[132:135], v[182:183], off
	s_nop 0
	global_load_dwordx4 v[128:131], v[182:183], off offset:256
	v_and_b32_e32 v182, 64, v180
	v_mov_b32_e32 v183, v161
	v_add_u32_e32 v204, 64, v182
	v_add_u32_e32 v182, v160, v170
	v_cmp_eq_u32_e32 vcc, 0, v194
	v_lshl_add_u64 v[194:195], v[182:183], 1, s[72:73]
	s_lshl_b32 s0, s0, 2
	v_xor_b32_e32 v171, 16, v180
	s_or_b32 s13, s0, s34
	v_cmp_lt_i32_e64 s[0:1], v171, v204
	v_add_u32_e32 v252, 0x40000, v160
	v_mov_b32_e32 v253, v161
	v_lshl_add_u64 v[252:253], v[252:253], 1, v[172:173]
	global_load_dwordx4 v[220:223], v[252:253], off
	global_load_dwordx4 v[224:227], v[252:253], off offset:256
	v_add_u32_e32 v252, 0x48000, v160
	v_mov_b32_e32 v253, v161
	v_lshl_add_u64 v[252:253], v[252:253], 1, v[172:173]
	global_load_dwordx4 v[228:231], v[252:253], off
	global_load_dwordx4 v[232:235], v[252:253], off offset:256
	v_add_u32_e32 v252, 0x50000, v160
	v_mov_b32_e32 v253, v161
	v_lshl_add_u64 v[252:253], v[252:253], 1, v[172:173]
	global_load_dwordx4 v[236:239], v[252:253], off
	global_load_dwordx4 v[240:243], v[252:253], off offset:256
	v_add_u32_e32 v252, 0x58000, v160
	v_mov_b32_e32 v253, v161
	v_lshl_add_u64 v[252:253], v[252:253], 1, v[172:173]
	global_load_dwordx4 v[244:247], v[252:253], off
	global_load_dwordx4 v[248:251], v[252:253], off offset:256
	s_waitcnt vmcnt(0)
	v_lshlrev_b32_e32 v196, 16, v186
	v_and_b32_e32 v197, 0xffff0000, v186
	v_lshlrev_b32_e32 v186, 16, v187
	v_and_b32_e32 v187, 0xffff0000, v187
	v_lshlrev_b32_e32 v198, 16, v188
	v_and_b32_e32 v199, 0xffff0000, v188
	v_lshlrev_b32_e32 v188, 16, v189
	v_and_b32_e32 v189, 0xffff0000, v189
	v_lshlrev_b32_e32 v200, 16, v190
	v_and_b32_e32 v201, 0xffff0000, v190
	v_lshlrev_b32_e32 v190, 16, v191
	v_and_b32_e32 v191, 0xffff0000, v191
	v_lshlrev_b32_e32 v202, 16, v192
	v_and_b32_e32 v203, 0xffff0000, v192
	v_lshlrev_b32_e32 v192, 16, v193
	v_and_b32_e32 v193, 0xffff0000, v193
	v_pk_add_f32 v[126:127], v[126:127], v[186:187]
	v_pk_add_f32 v[124:125], v[124:125], v[196:197]
	v_pk_add_f32 v[122:123], v[122:123], v[188:189]
	v_pk_add_f32 v[120:121], v[120:121], v[198:199]
	v_pk_add_f32 v[118:119], v[118:119], v[190:191]
	v_pk_add_f32 v[116:117], v[116:117], v[200:201]
	v_pk_add_f32 v[186:187], v[114:115], v[192:193]
	v_pk_add_f32 v[188:189], v[112:113], v[202:203]
	v_cvt_pk_bf16_f32 v112, v124, v125
	v_cvt_pk_bf16_f32 v113, v126, v127
	v_cvt_pk_bf16_f32 v114, v120, v121
	v_cvt_pk_bf16_f32 v115, v122, v123
	v_mul_f32_e32 v125, v125, v125
	v_mul_f32_e32 v127, v127, v127
	v_mul_f32_e32 v121, v121, v121
	v_mul_f32_e32 v123, v123, v123
	v_mul_f32_e32 v183, v117, v117
	v_mul_f32_e32 v190, v119, v119
	v_mul_f32_e32 v191, v189, v189
	v_mul_f32_e32 v192, v187, v187
	v_fmac_f32_e32 v125, v124, v124
	v_fmac_f32_e32 v127, v126, v126
	v_fmac_f32_e32 v121, v120, v120
	v_fmac_f32_e32 v123, v122, v122
	v_fmac_f32_e32 v183, v116, v116
	v_fmac_f32_e32 v190, v118, v118
	v_fmac_f32_e32 v191, v188, v188
	v_fmac_f32_e32 v192, v186, v186
	global_store_dwordx4 v[194:195], v[112:115], off
	v_cndmask_b32_e64 v171, v180, v171, s[0:1]
	v_add_u32_e32 v120, 0x80, v182
	v_add_f32_e32 v112, v125, v127
	v_add_f32_e32 v113, v121, v123
	v_add_f32_e32 v114, v183, v190
	v_add_f32_e32 v115, v191, v192
	v_add_f32_e32 v112, v112, v113
	v_add_f32_e32 v113, v114, v115
	v_add_f32_e32 v113, v112, v113
	v_lshlrev_b32_e32 v112, 2, v171
	v_mov_b32_e32 v121, v161
	v_lshl_add_u64 v[120:121], v[120:121], 1, s[72:73]
	v_cvt_pk_bf16_f32 v116, v116, v117
	v_cvt_pk_bf16_f32 v117, v118, v119
	s_waitcnt lgkmcnt(0)
	v_mov_b32_e32 v114, v113
	v_mov_b32_e32 v253, v113
	s_nop 1
	v_permlane16_swap_b32_e32 v114, v253
	v_add_f32_e32 v114, v114, v253
	v_xor_b32_e32 v113, 32, v180
	v_cmp_lt_i32_e64 s[0:1], v113, v204
	v_cvt_pk_bf16_f32 v118, v188, v189
	v_cvt_pk_bf16_f32 v119, v186, v187
	global_store_dwordx4 v[120:121], v[116:119], off
	s_nop 0
	v_cndmask_b32_e64 v113, v180, v113, s[0:1]
	v_lshlrev_b32_e32 v113, 2, v113
	v_mov_b32_e32 v115, v114
	v_mov_b32_e32 v253, v114
	s_nop 1
	v_permlane32_swap_b32_e32 v115, v253
	v_add_f32_e32 v116, v115, v253
	s_and_saveexec_b64 s[0:1], vcc
	s_cbranch_execz .LBB0_1285
	s_waitcnt lgkmcnt(0)
	v_lshl_add_u32 v114, v181, 5, s13
	v_mov_b32_e32 v115, v161
	v_lshl_add_u64 v[114:115], v[114:115], 2, s[76:77]
	global_store_dword v[114:115], v116, off

.LBB0_1291:
	s_or_b64 exec, exec, s[0:1]
	v_add_u32_e32 v64, 0x40000, v160
	s_waitcnt lgkmcnt(0)
	v_mov_b32_e32 v65, v161
	v_lshl_add_u64 v[64:65], v[64:65], 1, v[172:173]
	v_add_u32_e32 v64, 0x48000, v160
	v_mov_b32_e32 v65, v161
	v_add_u32_e32 v66, 0x50000, v160
	v_mov_b32_e32 v67, v161
	v_add_u32_e32 v160, 0x58000, v160
	v_lshl_add_u64 v[64:65], v[64:65], 1, v[172:173]
	v_lshl_add_u64 v[66:67], v[66:67], 1, v[172:173]
	v_lshl_add_u64 v[88:89], v[160:161], 1, v[172:173]
	s_nop 0
	v_add_u32_e32 v88, 0x80, v181
	v_lshl_add_u32 v160, v88, 11, v170
	v_lshl_add_u64 v[98:99], v[160:161], 1, s[72:73]
	v_add_u32_e32 v160, 0x80, v160
	s_waitcnt vmcnt(7)
	v_lshlrev_b32_e32 v100, 16, v220
	v_and_b32_e32 v101, 0xffff0000, v220
	v_lshlrev_b32_e32 v220, 16, v221
	v_and_b32_e32 v221, 0xffff0000, v221
	v_lshlrev_b32_e32 v102, 16, v222
	v_and_b32_e32 v103, 0xffff0000, v222
	v_lshlrev_b32_e32 v222, 16, v223
	v_and_b32_e32 v223, 0xffff0000, v223
	s_waitcnt vmcnt(6)
	v_lshlrev_b32_e32 v104, 16, v224
	v_and_b32_e32 v105, 0xffff0000, v224
	v_lshlrev_b32_e32 v224, 16, v225
	v_and_b32_e32 v225, 0xffff0000, v225
	v_lshlrev_b32_e32 v106, 16, v226
	v_and_b32_e32 v107, 0xffff0000, v226
	v_lshlrev_b32_e32 v226, 16, v227
	v_and_b32_e32 v227, 0xffff0000, v227
	v_pk_add_f32 v[62:63], v[62:63], v[220:221]
	v_pk_add_f32 v[60:61], v[60:61], v[100:101]
	v_pk_add_f32 v[58:59], v[58:59], v[222:223]
	v_pk_add_f32 v[56:57], v[56:57], v[102:103]
	v_pk_add_f32 v[54:55], v[54:55], v[224:225]
	v_pk_add_f32 v[52:53], v[52:53], v[104:105]
	v_pk_add_f32 v[220:221], v[50:51], v[226:227]
	v_pk_add_f32 v[222:223], v[48:49], v[106:107]
	v_cvt_pk_bf16_f32 v48, v60, v61
	v_cvt_pk_bf16_f32 v49, v62, v63
	v_cvt_pk_bf16_f32 v50, v56, v57
	v_cvt_pk_bf16_f32 v51, v58, v59
	v_mul_f32_e32 v61, v61, v61
	v_mul_f32_e32 v63, v63, v63
	v_mul_f32_e32 v57, v57, v57
	v_mul_f32_e32 v59, v59, v59
	v_mul_f32_e32 v89, v53, v53
	v_mul_f32_e32 v224, v55, v55
	v_mul_f32_e32 v225, v223, v223
	v_mul_f32_e32 v226, v221, v221
	v_fmac_f32_e32 v61, v60, v60
	v_fmac_f32_e32 v63, v62, v62
	v_fmac_f32_e32 v57, v56, v56
	v_fmac_f32_e32 v59, v58, v58
	v_fmac_f32_e32 v89, v52, v52
	v_fmac_f32_e32 v224, v54, v54
	v_fmac_f32_e32 v225, v222, v222
	v_fmac_f32_e32 v226, v220, v220
	v_add_f32_e32 v56, v61, v63
	v_add_f32_e32 v57, v57, v59
	v_add_f32_e32 v58, v89, v224
	v_add_f32_e32 v59, v225, v226
	v_add_f32_e32 v56, v56, v57
	v_add_f32_e32 v57, v58, v59
	v_add_f32_e32 v56, v56, v57
	global_store_dwordx4 v[98:99], v[48:51], off
	s_nop 1
	v_cvt_pk_bf16_f32 v50, v52, v53
	s_waitcnt lgkmcnt(0)
	v_mov_b32_e32 v57, v56
	v_mov_b32_e32 v253, v56
	s_nop 1
	v_permlane16_swap_b32_e32 v57, v253
	v_add_f32_e32 v48, v57, v253
	v_cvt_pk_bf16_f32 v51, v54, v55
	v_lshl_add_u64 v[54:55], v[160:161], 1, s[72:73]
	v_cvt_pk_bf16_f32 v52, v222, v223
	v_cvt_pk_bf16_f32 v53, v220, v221
	global_store_dwordx4 v[54:55], v[50:53], off
	v_mov_b32_e32 v49, v48
	v_mov_b32_e32 v253, v48
	s_nop 1
	v_permlane32_swap_b32_e32 v49, v253
	v_add_f32_e32 v50, v49, v253
	s_and_saveexec_b64 s[0:1], vcc
	s_cbranch_execz .LBB0_1293
	v_lshl_add_u32 v160, v88, 5, s13
	s_waitcnt lgkmcnt(0)
	v_lshl_add_u64 v[48:49], v[160:161], 2, s[76:77]
	global_store_dword v[48:49], v50, off
.LBB0_1293:
	s_or_b64 exec, exec, s[0:1]
	s_waitcnt vmcnt(7)
	v_lshlrev_b32_e32 v50, 16, v228
	v_and_b32_e32 v51, 0xffff0000, v228
	v_lshlrev_b32_e32 v52, 16, v229
	v_and_b32_e32 v53, 0xffff0000, v229
	v_lshlrev_b32_e32 v54, 16, v230
	v_and_b32_e32 v55, 0xffff0000, v230
	v_pk_add_f32 v[44:45], v[44:45], v[50:51]
	v_pk_add_f32 v[46:47], v[46:47], v[52:53]
	v_pk_add_f32 v[52:53], v[40:41], v[54:55]
	v_cvt_pk_bf16_f32 v40, v44, v45
	v_mul_f32_e32 v45, v45, v45
	v_lshlrev_b32_e32 v56, 16, v231
	v_and_b32_e32 v57, 0xffff0000, v231
	v_fmac_f32_e32 v45, v44, v44
	v_mul_f32_e32 v44, v47, v47
	v_pk_add_f32 v[50:51], v[42:43], v[56:57]
	v_fmac_f32_e32 v44, v46, v46
	v_cvt_pk_bf16_f32 v41, v46, v47
	v_add_f32_e32 v44, v45, v44
	v_mul_f32_e32 v45, v53, v53
	v_mul_f32_e32 v46, v51, v51
	v_fmac_f32_e32 v45, v52, v52
	v_fmac_f32_e32 v46, v50, v50
	v_add_f32_e32 v45, v45, v46
	s_waitcnt lgkmcnt(0)
	v_add_f32_e32 v49, v44, v45
	s_waitcnt vmcnt(6)
	v_lshlrev_b32_e32 v44, 16, v232
	v_and_b32_e32 v45, 0xffff0000, v232
	v_lshlrev_b32_e32 v46, 16, v233
	v_and_b32_e32 v47, 0xffff0000, v233
	v_cvt_pk_bf16_f32 v42, v52, v53
	v_cvt_pk_bf16_f32 v43, v50, v51
	v_lshlrev_b32_e32 v50, 16, v234
	v_and_b32_e32 v51, 0xffff0000, v234
	v_pk_add_f32 v[38:39], v[38:39], v[46:47]
	v_pk_add_f32 v[36:37], v[36:37], v[44:45]
	v_lshlrev_b32_e32 v52, 16, v235
	v_and_b32_e32 v53, 0xffff0000, v235
	v_pk_add_f32 v[46:47], v[32:33], v[50:51]
	v_mul_f32_e32 v32, v37, v37
	v_mul_f32_e32 v33, v39, v39
	v_pk_add_f32 v[44:45], v[34:35], v[52:53]
	v_fmac_f32_e32 v32, v36, v36
	v_fmac_f32_e32 v33, v38, v38
	v_add_f32_e32 v32, v32, v33
	v_mul_f32_e32 v33, v47, v47
	v_mul_f32_e32 v34, v45, v45
	v_fmac_f32_e32 v33, v46, v46
	v_fmac_f32_e32 v34, v44, v44
	v_add_f32_e32 v33, v33, v34
	v_add_f32_e32 v32, v32, v33
	v_add_f32_e32 v32, v49, v32
	v_add_u32_e32 v48, 0x90, v181
	v_lshl_add_u32 v160, v48, 11, v170
	v_lshl_add_u64 v[54:55], v[160:161], 1, s[72:73]
	v_add_u32_e32 v160, 0x80, v160
	s_waitcnt lgkmcnt(0)
	v_mov_b32_e32 v33, v32
	v_mov_b32_e32 v253, v32
	s_nop 1
	v_permlane16_swap_b32_e32 v33, v253
	v_add_f32_e32 v32, v33, v253
	global_store_dwordx4 v[54:55], v[40:43], off
	v_cvt_pk_bf16_f32 v34, v36, v37
	v_cvt_pk_bf16_f32 v35, v38, v39
	v_lshl_add_u64 v[38:39], v[160:161], 1, s[72:73]
	v_cvt_pk_bf16_f32 v36, v46, v47
	v_cvt_pk_bf16_f32 v37, v44, v45
	global_store_dwordx4 v[38:39], v[34:37], off
	v_mov_b32_e32 v33, v32
	v_mov_b32_e32 v253, v32
	s_nop 1
	v_permlane32_swap_b32_e32 v33, v253
	v_add_f32_e32 v34, v33, v253
	s_and_saveexec_b64 s[0:1], vcc
	s_cbranch_execz .LBB0_1295
	v_lshl_add_u32 v160, v48, 5, s13
	s_waitcnt lgkmcnt(0)
	v_lshl_add_u64 v[32:33], v[160:161], 2, s[76:77]
	global_store_dword v[32:33], v34, off
.LBB0_1295:
	s_or_b64 exec, exec, s[0:1]
	s_waitcnt vmcnt(7)
	v_lshlrev_b32_e32 v34, 16, v236
	v_and_b32_e32 v35, 0xffff0000, v236
	v_lshlrev_b32_e32 v36, 16, v237
	v_and_b32_e32 v37, 0xffff0000, v237
	v_lshlrev_b32_e32 v38, 16, v238
	v_and_b32_e32 v39, 0xffff0000, v238
	v_pk_add_f32 v[28:29], v[28:29], v[34:35]
	v_pk_add_f32 v[30:31], v[30:31], v[36:37]
	v_pk_add_f32 v[36:37], v[24:25], v[38:39]
	v_cvt_pk_bf16_f32 v24, v28, v29
	v_mul_f32_e32 v29, v29, v29
	v_lshlrev_b32_e32 v40, 16, v239
	v_and_b32_e32 v41, 0xffff0000, v239
	v_fmac_f32_e32 v29, v28, v28
	v_mul_f32_e32 v28, v31, v31
	v_pk_add_f32 v[34:35], v[26:27], v[40:41]
	v_fmac_f32_e32 v28, v30, v30
	v_cvt_pk_bf16_f32 v25, v30, v31
	v_add_f32_e32 v28, v29, v28
	v_mul_f32_e32 v29, v37, v37
	v_mul_f32_e32 v30, v35, v35
	v_fmac_f32_e32 v29, v36, v36
	v_fmac_f32_e32 v30, v34, v34
	v_add_f32_e32 v29, v29, v30
	s_waitcnt lgkmcnt(0)
	v_add_f32_e32 v33, v28, v29
	s_waitcnt vmcnt(6)
	v_lshlrev_b32_e32 v28, 16, v240
	v_and_b32_e32 v29, 0xffff0000, v240
	v_lshlrev_b32_e32 v30, 16, v241
	v_and_b32_e32 v31, 0xffff0000, v241
	v_cvt_pk_bf16_f32 v26, v36, v37
	v_cvt_pk_bf16_f32 v27, v34, v35
	v_lshlrev_b32_e32 v34, 16, v242
	v_and_b32_e32 v35, 0xffff0000, v242
	v_pk_add_f32 v[22:23], v[22:23], v[30:31]
	v_pk_add_f32 v[20:21], v[20:21], v[28:29]
	v_lshlrev_b32_e32 v36, 16, v243
	v_and_b32_e32 v37, 0xffff0000, v243
	v_pk_add_f32 v[30:31], v[16:17], v[34:35]
	v_mul_f32_e32 v16, v21, v21
	v_mul_f32_e32 v17, v23, v23
	v_pk_add_f32 v[28:29], v[18:19], v[36:37]
	v_fmac_f32_e32 v16, v20, v20
	v_fmac_f32_e32 v17, v22, v22
	v_add_f32_e32 v16, v16, v17
	v_mul_f32_e32 v17, v31, v31
	v_mul_f32_e32 v18, v29, v29
	v_fmac_f32_e32 v17, v30, v30
	v_fmac_f32_e32 v18, v28, v28
	v_add_f32_e32 v17, v17, v18
	v_add_f32_e32 v16, v16, v17
	v_add_f32_e32 v16, v33, v16
	v_add_u32_e32 v32, 0xa0, v181
	v_lshl_add_u32 v160, v32, 11, v170
	v_lshl_add_u64 v[38:39], v[160:161], 1, s[72:73]
	v_add_u32_e32 v160, 0x80, v160
	s_waitcnt lgkmcnt(0)
	v_mov_b32_e32 v17, v16
	v_mov_b32_e32 v253, v16
	s_nop 1
	v_permlane16_swap_b32_e32 v17, v253
	v_add_f32_e32 v16, v17, v253
	global_store_dwordx4 v[38:39], v[24:27], off
	v_cvt_pk_bf16_f32 v18, v20, v21
	v_cvt_pk_bf16_f32 v19, v22, v23
	v_lshl_add_u64 v[22:23], v[160:161], 1, s[72:73]
	v_cvt_pk_bf16_f32 v20, v30, v31
	v_cvt_pk_bf16_f32 v21, v28, v29
	global_store_dwordx4 v[22:23], v[18:21], off
	v_mov_b32_e32 v17, v16
	v_mov_b32_e32 v253, v16
	s_nop 1
	v_permlane32_swap_b32_e32 v17, v253
	v_add_f32_e32 v18, v17, v253
	s_and_saveexec_b64 s[0:1], vcc
	s_cbranch_execz .LBB0_1297
	v_lshl_add_u32 v160, v32, 5, s13
	s_waitcnt lgkmcnt(0)
	v_lshl_add_u64 v[16:17], v[160:161], 2, s[76:77]
	global_store_dword v[16:17], v18, off
.LBB0_1297:
	s_or_b64 exec, exec, s[0:1]
	s_waitcnt vmcnt(7)
	v_lshlrev_b32_e32 v18, 16, v244
	v_and_b32_e32 v19, 0xffff0000, v244
	v_lshlrev_b32_e32 v20, 16, v245
	v_and_b32_e32 v21, 0xffff0000, v245
	v_lshlrev_b32_e32 v22, 16, v246
	v_and_b32_e32 v23, 0xffff0000, v246
	v_pk_add_f32 v[12:13], v[12:13], v[18:19]
	v_pk_add_f32 v[14:15], v[14:15], v[20:21]
	v_pk_add_f32 v[20:21], v[8:9], v[22:23]
	v_cvt_pk_bf16_f32 v8, v12, v13
	v_mul_f32_e32 v13, v13, v13
	v_lshlrev_b32_e32 v24, 16, v247
	v_and_b32_e32 v25, 0xffff0000, v247
	v_fmac_f32_e32 v13, v12, v12
	v_mul_f32_e32 v12, v15, v15
	v_pk_add_f32 v[18:19], v[10:11], v[24:25]
	v_fmac_f32_e32 v12, v14, v14
	v_cvt_pk_bf16_f32 v9, v14, v15
	v_add_f32_e32 v12, v13, v12
	v_mul_f32_e32 v13, v21, v21
	v_mul_f32_e32 v14, v19, v19
	v_fmac_f32_e32 v13, v20, v20
	v_fmac_f32_e32 v14, v18, v18
	v_add_f32_e32 v13, v13, v14
	s_waitcnt lgkmcnt(0)
	v_add_f32_e32 v17, v12, v13
	s_waitcnt vmcnt(6)
	v_lshlrev_b32_e32 v12, 16, v248
	v_and_b32_e32 v13, 0xffff0000, v248
	v_lshlrev_b32_e32 v14, 16, v249
	v_and_b32_e32 v15, 0xffff0000, v249
	v_cvt_pk_bf16_f32 v10, v20, v21
	v_cvt_pk_bf16_f32 v11, v18, v19
	v_lshlrev_b32_e32 v18, 16, v250
	v_and_b32_e32 v19, 0xffff0000, v250
	v_pk_add_f32 v[6:7], v[6:7], v[14:15]
	v_pk_add_f32 v[4:5], v[4:5], v[12:13]
	v_lshlrev_b32_e32 v20, 16, v251
	v_and_b32_e32 v21, 0xffff0000, v251
	v_pk_add_f32 v[14:15], v[0:1], v[18:19]
	v_mul_f32_e32 v0, v5, v5
	v_mul_f32_e32 v1, v7, v7
	v_pk_add_f32 v[12:13], v[2:3], v[20:21]
	v_fmac_f32_e32 v0, v4, v4
	v_fmac_f32_e32 v1, v6, v6
	v_add_f32_e32 v0, v0, v1
	v_mul_f32_e32 v1, v15, v15
	v_mul_f32_e32 v2, v13, v13
	v_fmac_f32_e32 v1, v14, v14
	v_fmac_f32_e32 v2, v12, v12
	v_add_f32_e32 v1, v1, v2
	v_add_f32_e32 v0, v0, v1
	v_add_f32_e32 v0, v17, v0
	v_add_u32_e32 v16, 0xb0, v181
	v_lshl_add_u32 v160, v16, 11, v170
	v_lshl_add_u64 v[22:23], v[160:161], 1, s[72:73]
	v_add_u32_e32 v160, 0x80, v160
	s_waitcnt lgkmcnt(0)
	v_mov_b32_e32 v1, v0
	v_mov_b32_e32 v253, v0
	s_nop 1
	v_permlane16_swap_b32_e32 v1, v253
	v_add_f32_e32 v0, v1, v253
	global_store_dwordx4 v[22:23], v[8:11], off
	v_cvt_pk_bf16_f32 v2, v4, v5
	v_cvt_pk_bf16_f32 v3, v6, v7
	v_lshl_add_u64 v[6:7], v[160:161], 1, s[72:73]
	v_cvt_pk_bf16_f32 v4, v14, v15
	v_cvt_pk_bf16_f32 v5, v12, v13
	global_store_dwordx4 v[6:7], v[2:5], off
	v_mov_b32_e32 v1, v0
	v_mov_b32_e32 v253, v0
	s_nop 1
	v_permlane32_swap_b32_e32 v1, v253
	v_add_f32_e32 v2, v1, v253
	s_and_saveexec_b64 s[0:1], vcc
	s_cbranch_execz .LBB0_1299
	v_lshl_add_u32 v160, v16, 5, s13
	s_waitcnt lgkmcnt(0)
	v_lshl_add_u64 v[0:1], v[160:161], 2, s[76:77]
	global_store_dword v[0:1], v2, off
